# grid barrier: non-leader workgroups wait on the top-level generation word directly (one hop less per seam)
# speedup vs baseline: 1.0282x; 1.0002x over previous
.LBB0_134:
	s_or_b64 exec, exec, s[6:7]
	v_cvt_f32_u32_e32 v5, v3
	s_waitcnt vmcnt(0)
	v_readfirstlane_b32 s4, v4
	v_sub_u32_e32 v4, 0, v3
	v_rcp_iflag_f32_e32 v5, v5
	v_add_u32_e32 v6, s4, v2
	v_mul_f32_e32 v5, 0x4f7ffffe, v5
	v_cvt_u32_f32_e32 v5, v5
	v_mul_lo_u32 v2, v4, v5
	v_mul_hi_u32 v2, v5, v2
	v_add_u32_e32 v2, v5, v2
	v_mul_hi_u32 v2, v6, v2
	v_mul_lo_u32 v4, v2, v3
	v_sub_u32_e32 v4, v6, v4
	v_add_u32_e32 v5, 1, v2
	v_cmp_ge_u32_e32 vcc, v4, v3
	s_nop 1
	v_cndmask_b32_e32 v2, v2, v5, vcc
	v_sub_u32_e32 v5, v4, v3
	v_cndmask_b32_e32 v4, v4, v5, vcc
	v_add_u32_e32 v5, 1, v2
	v_cmp_ge_u32_e32 vcc, v4, v3
	v_add_u32_e32 v4, 1, v6
	s_nop 0
	v_cndmask_b32_e32 v2, v2, v5, vcc
	v_mul_lo_u32 v5, v3, v2
	v_add_u32_e32 v3, v5, v3
	v_cmp_ne_u32_e32 vcc, v4, v3
	s_and_saveexec_b64 s[4:5], vcc
	s_xor_b64 s[4:5], exec, s[4:5]
	s_cbranch_execz .LBB0_148
	s_waitcnt lgkmcnt(0)
	s_add_u32 s10, s20, 0x1a02dd00
	s_addc_u32 s11, s21, 0
	v_mov_b32_e32 v1, 0
	global_load_dword v1, v1, s[10:11] sc1
	s_waitcnt vmcnt(0)
	v_cmp_eq_u32_e32 vcc, v1, v2
	s_and_saveexec_b64 s[6:7], vcc
	s_cbranch_execz .LBB0_147
	s_add_u32 s8, s20, 0x1a02aa00
	s_addc_u32 s9, s21, 0
	s_mov_b32 s30, 1
	s_mov_b64 s[12:13], 0
	v_mov_b32_e32 v1, 0
	s_branch .LBB0_138

.LBB0_669:
	s_or_b64 exec, exec, s[6:7]
	v_cvt_f32_u32_e32 v5, v3
	s_waitcnt vmcnt(0)
	v_readfirstlane_b32 s4, v4
	v_sub_u32_e32 v4, 0, v3
	v_rcp_iflag_f32_e32 v5, v5
	v_add_u32_e32 v6, s4, v2
	v_mul_f32_e32 v5, 0x4f7ffffe, v5
	v_cvt_u32_f32_e32 v5, v5
	v_mul_lo_u32 v2, v4, v5
	v_mul_hi_u32 v2, v5, v2
	v_add_u32_e32 v2, v5, v2
	v_mul_hi_u32 v2, v6, v2
	v_mul_lo_u32 v4, v2, v3
	v_sub_u32_e32 v4, v6, v4
	v_add_u32_e32 v5, 1, v2
	v_cmp_ge_u32_e32 vcc, v4, v3
	s_nop 1
	v_cndmask_b32_e32 v2, v2, v5, vcc
	v_sub_u32_e32 v5, v4, v3
	v_cndmask_b32_e32 v4, v4, v5, vcc
	v_add_u32_e32 v5, 1, v2
	v_cmp_ge_u32_e32 vcc, v4, v3
	v_add_u32_e32 v4, 1, v6
	s_nop 0
	v_cndmask_b32_e32 v2, v2, v5, vcc
	v_mul_lo_u32 v5, v3, v2
	v_add_u32_e32 v3, v5, v3
	v_cmp_ne_u32_e32 vcc, v4, v3
	s_and_saveexec_b64 s[4:5], vcc
	s_xor_b64 s[4:5], exec, s[4:5]
	s_cbranch_execz .LBB0_683
	s_waitcnt lgkmcnt(0)
	s_add_u32 s10, s20, 0x1a02dd00
	s_addc_u32 s11, s21, 0
	v_mov_b32_e32 v1, 0
	global_load_dword v1, v1, s[10:11] sc1
	s_waitcnt vmcnt(0)
	v_cmp_eq_u32_e32 vcc, v1, v2
	s_and_saveexec_b64 s[6:7], vcc
	s_cbranch_execz .LBB0_682
	s_add_u32 s8, s20, 0x1a02aa00
	s_addc_u32 s9, s21, 0
	s_mov_b32 s28, 1
	s_mov_b64 s[12:13], 0
	v_mov_b32_e32 v1, 0
	s_branch .LBB0_673
